# adds: next tile's A half-tile staged ahead of the epilogue stores in the last K iteration so the first K-tile's second wait stays relaxed (multi-tile phases)
# baseline (speedup 1.0000x reference)
; #define PG8_STAGE(bufoff, gbase, voff) do { _Pragma("unroll") for (int _i = 0; _i < 2; ++_i) \
;         __builtin_amdgcn_global_load_lds((const unsigned*)((const char*)(gbase) + (voff)[_i]), (LAS unsigned*)(lds + (bufoff) + ldsw + _i * 8192), 16, 0, 0); } while (0)
; #define PG8_LDA(dst, b, h) do { _Pragma("unroll") for (int m = 0; m < 4; ++m) _Pragma("unroll") for (int k = 0; k < 2; ++k) dst[m][k] = *(const LAS bf16x8*)(lds + PG8_SA(b, h) + aoff + m * 2048 + k * 1024); } while (0)
; #define PG8_MMA(ai, bj, At, Bt) do { __builtin_amdgcn_s_setprio(1); _Pragma("unroll") for (int m = 0; m < 4; ++m) _Pragma("unroll") for (int n = 0; n < 2; ++n) _Pragma("unroll") for (int k = 0; k < 2; ++k) \
;         acc[ai][bj][m][n] = __builtin_amdgcn_mfma_f32_16x16x32_bf16(Bt[n][k], At[m][k], acc[ai][bj][m][n], 0, 0, 0); __builtin_amdgcn_s_setprio(0); } while (0)
; #define PG8_WAIT_V(n) asm volatile("s_waitcnt vmcnt(" #n ")" ::: "memory")
; #define PG8_WAIT_L(n) asm volatile("s_waitcnt lgkmcnt(" #n ")" ::: "memory")
; #define PG8_BAR __builtin_amdgcn_s_barrier()
; #define PG8_WAIT_RELAX(flag, n) asm volatile("s_cmp_eq_u32 %0, 0\n\ts_cbranch_scc1 .Lrw%=\n\ts_waitcnt vmcnt(8)\n.Lrw%=:\n\ts_waitcnt vmcnt(%1)" :: "s"(flag), "n"(n) : "scc", "memory")
; #define PG8_SCHED __builtin_amdgcn_sched_barrier(0)
; template <class Epi, bool ALIGN_EPI = true>
; __device__ __forceinline__ void gemm_phase(LAS unsigned char* lds, const Gemm g, const Sched& S, const Epi& E) {
;     ...
;             PG8_WAIT_L(0); PG8_BAR; PG8_MMA(0, 0, At, B0); PG8_MMA(0, 1, At, B1); PG8_BAR; PG8_SCHED;
;             PG8_LDA(At, 0, 1); PG8_STAGE(PG8_SB(0, 0), b2, voffB); PG8_STAGE(PG8_SB(0, 1), b2 + hstepB, voffB); PG8_STAGE(PG8_SA(0, 0), a2, voffA);
;             if constexpr (Epi::NSTORES > 0) PG8_WAIT_RELAX(rflag, 8 + Epi::NSTORES); else PG8_WAIT_V(8);
;             PG8_WAIT_L(0); PG8_BAR; PG8_MMA(1, 0, At, B0); PG8_MMA(1, 1, At, B1); PG8_BAR; PG8_SCHED;
.Lrw6:
	s_waitcnt vmcnt(24) lgkmcnt(0)
	s_barrier
	s_setprio 1
	v_mfma_f32_16x16x32_bf16 v[130:133], v[134:137], v[178:181], v[130:133]
	v_mfma_f32_16x16x32_bf16 v[126:129], v[142:145], v[178:181], v[126:129]
	v_mfma_f32_16x16x32_bf16 v[122:125], v[134:137], v[192:195], v[122:125]
	v_mfma_f32_16x16x32_bf16 v[118:121], v[142:145], v[192:195], v[118:121]
	v_mfma_f32_16x16x32_bf16 v[114:117], v[134:137], v[224:227], v[114:117]
	v_mfma_f32_16x16x32_bf16 v[110:113], v[142:145], v[224:227], v[110:113]
	v_mfma_f32_16x16x32_bf16 v[106:109], v[134:137], v[232:235], v[106:109]
	v_mfma_f32_16x16x32_bf16 v[102:105], v[142:145], v[232:235], v[102:105]
	v_mfma_f32_16x16x32_bf16 v[130:133], v[138:141], v[188:191], v[130:133]
	v_mfma_f32_16x16x32_bf16 v[126:129], v[146:149], v[188:191], v[126:129]
	v_mfma_f32_16x16x32_bf16 v[122:125], v[138:141], v[206:209], v[122:125]
	v_mfma_f32_16x16x32_bf16 v[118:121], v[146:149], v[206:209], v[118:121]
	v_mfma_f32_16x16x32_bf16 v[114:117], v[138:141], v[228:231], v[114:117]
	v_mfma_f32_16x16x32_bf16 v[110:113], v[146:149], v[228:231], v[110:113]
	v_mfma_f32_16x16x32_bf16 v[106:109], v[138:141], v[236:239], v[106:109]
	v_mfma_f32_16x16x32_bf16 v[102:105], v[146:149], v[236:239], v[102:105]
	s_setprio 0
	s_setprio 1
	v_mfma_f32_16x16x32_bf16 v[98:101], v[162:165], v[178:181], v[98:101]
	v_mfma_f32_16x16x32_bf16 v[94:97], v[170:173], v[178:181], v[94:97]
	v_mfma_f32_16x16x32_bf16 v[90:93], v[162:165], v[192:195], v[90:93]
	v_mfma_f32_16x16x32_bf16 v[86:89], v[170:173], v[192:195], v[86:89]
	v_mfma_f32_16x16x32_bf16 v[82:85], v[162:165], v[224:227], v[82:85]
	v_mfma_f32_16x16x32_bf16 v[78:81], v[170:173], v[224:227], v[78:81]
	v_mfma_f32_16x16x32_bf16 v[74:77], v[162:165], v[232:235], v[74:77]
	v_mfma_f32_16x16x32_bf16 v[70:73], v[170:173], v[232:235], v[70:73]
	v_mfma_f32_16x16x32_bf16 v[98:101], v[166:169], v[188:191], v[98:101]
	v_mfma_f32_16x16x32_bf16 v[94:97], v[174:177], v[188:191], v[94:97]
	v_mfma_f32_16x16x32_bf16 v[90:93], v[166:169], v[206:209], v[90:93]
	v_mfma_f32_16x16x32_bf16 v[86:89], v[174:177], v[206:209], v[86:89]
	v_mfma_f32_16x16x32_bf16 v[82:85], v[166:169], v[228:231], v[82:85]
	v_mfma_f32_16x16x32_bf16 v[78:81], v[174:177], v[228:231], v[78:81]
	v_mfma_f32_16x16x32_bf16 v[74:77], v[166:169], v[236:239], v[74:77]
	v_mfma_f32_16x16x32_bf16 v[70:73], v[174:177], v[236:239], v[70:73]
	s_setprio 0
	s_barrier
	s_add_u32 s24, s6, 0x80000
	s_addc_u32 s25, s7, 0
	ds_read_b128 v[178:181], v186 offset:16384
	ds_read_b128 v[188:191], v186 offset:17408
	ds_read_b128 v[192:195], v186 offset:18432
	ds_read_b128 v[206:209], v186 offset:19456
	s_add_i32 m0, s27, 0x10000
	ds_read_b128 v[224:227], v186 offset:20480
	global_load_lds_dwordx4 v152, s[6:7]
	s_add_i32 m0, s27, 0x12000
	ds_read_b128 v[228:231], v186 offset:21504
	global_load_lds_dwordx4 v156, s[6:7]
	s_add_i32 m0, s27, 0x14000
	ds_read_b128 v[232:235], v186 offset:22528
	global_load_lds_dwordx4 v152, s[24:25]
	s_add_i32 m0, s27, 0x16000
	ds_read_b128 v[236:239], v186 offset:23552
	global_load_lds_dwordx4 v156, s[24:25]
	s_cmp_eq_u32 s53, 0
	s_cbranch_scc1 .Lrw7
	s_waitcnt vmcnt(6)
.Lrw7:
	s_waitcnt vmcnt(24) lgkmcnt(0)
	s_barrier
	s_setprio 1
	v_mfma_f32_16x16x32_bf16 v[66:69], v[134:137], v[178:181], v[66:69]
	v_mfma_f32_16x16x32_bf16 v[62:65], v[142:145], v[178:181], v[62:65]
	v_mfma_f32_16x16x32_bf16 v[58:61], v[134:137], v[192:195], v[58:61]
	v_mfma_f32_16x16x32_bf16 v[54:57], v[142:145], v[192:195], v[54:57]
	v_mfma_f32_16x16x32_bf16 v[50:53], v[134:137], v[224:227], v[50:53]
	v_mfma_f32_16x16x32_bf16 v[46:49], v[142:145], v[224:227], v[46:49]
	v_mfma_f32_16x16x32_bf16 v[42:45], v[134:137], v[232:235], v[42:45]
	v_mfma_f32_16x16x32_bf16 v[38:41], v[142:145], v[232:235], v[38:41]
	v_mfma_f32_16x16x32_bf16 v[66:69], v[138:141], v[188:191], v[66:69]
	v_mfma_f32_16x16x32_bf16 v[62:65], v[146:149], v[188:191], v[62:65]
	v_mfma_f32_16x16x32_bf16 v[58:61], v[138:141], v[206:209], v[58:61]
	v_mfma_f32_16x16x32_bf16 v[54:57], v[146:149], v[206:209], v[54:57]
	v_mfma_f32_16x16x32_bf16 v[50:53], v[138:141], v[228:231], v[50:53]
	v_mfma_f32_16x16x32_bf16 v[46:49], v[146:149], v[228:231], v[46:49]
	v_mfma_f32_16x16x32_bf16 v[42:45], v[138:141], v[236:239], v[42:45]
	v_mfma_f32_16x16x32_bf16 v[38:41], v[146:149], v[236:239], v[38:41]
	s_setprio 0
	s_setprio 1
	v_mfma_f32_16x16x32_bf16 v[34:37], v[162:165], v[178:181], v[34:37]
	v_mfma_f32_16x16x32_bf16 v[30:33], v[170:173], v[178:181], v[30:33]
	v_mfma_f32_16x16x32_bf16 v[26:29], v[162:165], v[192:195], v[26:29]
	v_mfma_f32_16x16x32_bf16 v[22:25], v[170:173], v[192:195], v[22:25]
	v_mfma_f32_16x16x32_bf16 v[18:21], v[162:165], v[224:227], v[18:21]
	v_mfma_f32_16x16x32_bf16 v[14:17], v[170:173], v[224:227], v[14:17]
	v_mfma_f32_16x16x32_bf16 v[10:13], v[162:165], v[232:235], v[10:13]
	v_mfma_f32_16x16x32_bf16 v[4:7], v[170:173], v[232:235], v[6:9]
	v_mfma_f32_16x16x32_bf16 v[34:37], v[166:169], v[188:191], v[34:37]
	v_mfma_f32_16x16x32_bf16 v[30:33], v[174:177], v[188:191], v[30:33]
	v_mfma_f32_16x16x32_bf16 v[26:29], v[166:169], v[206:209], v[26:29]
	v_mfma_f32_16x16x32_bf16 v[22:25], v[174:177], v[206:209], v[22:25]
	v_mfma_f32_16x16x32_bf16 v[18:21], v[166:169], v[228:231], v[18:21]
	v_mfma_f32_16x16x32_bf16 v[14:17], v[174:177], v[228:231], v[14:17]
	v_mfma_f32_16x16x32_bf16 v[10:13], v[166:169], v[236:239], v[10:13]
	v_mfma_f32_16x16x32_bf16 v[4:7], v[174:177], v[236:239], v[4:7]
	s_setprio 0
	s_barrier
; #define PG8_STAGE(bufoff, gbase, voff) do { _Pragma("unroll") for (int _i = 0; _i < 2; ++_i) \
;         __builtin_amdgcn_global_load_lds((const unsigned*)((const char*)(gbase) + (voff)[_i]), (LAS unsigned*)(lds + (bufoff) + ldsw + _i * 8192), 16, 0, 0); } while (0)
; #define PG8_LDA(dst, b, h) do { _Pragma("unroll") for (int m = 0; m < 4; ++m) _Pragma("unroll") for (int k = 0; k < 2; ++k) dst[m][k] = *(const LAS bf16x8*)(lds + PG8_SA(b, h) + aoff + m * 2048 + k * 1024); } while (0)
; #define PG8_LDB(dst, b, h) do { _Pragma("unroll") for (int n = 0; n < 2; ++n) _Pragma("unroll") for (int k = 0; k < 2; ++k) dst[n][k] = *(const LAS bf16x8*)(lds + PG8_SB(b, h) + boff + n * 2048 + k * 1024); } while (0)
; #define PG8_MMA(ai, bj, At, Bt) do { __builtin_amdgcn_s_setprio(1); _Pragma("unroll") for (int m = 0; m < 4; ++m) _Pragma("unroll") for (int n = 0; n < 2; ++n) _Pragma("unroll") for (int k = 0; k < 2; ++k) \
;         acc[ai][bj][m][n] = __builtin_amdgcn_mfma_f32_16x16x32_bf16(Bt[n][k], At[m][k], acc[ai][bj][m][n], 0, 0, 0); __builtin_amdgcn_s_setprio(0); } while (0)
; #define PG8_WAIT_V(n) asm volatile("s_waitcnt vmcnt(" #n ")" ::: "memory")
; #define PG8_WAIT_L(n) asm volatile("s_waitcnt lgkmcnt(" #n ")" ::: "memory")
; #define PG8_BAR __builtin_amdgcn_s_barrier()
; #define PG8_SCHED __builtin_amdgcn_sched_barrier(0)
; template <class Epi, bool ALIGN_EPI = true>
; __device__ __forceinline__ void gemm_phase(LAS unsigned char* lds, const Gemm g, const Sched& S, const Epi& E) {
;     ...
;             PG8_LDB(B0, 1, 0); PG8_LDB(B1, 1, 1); PG8_SCHED; PG8_LDA(At, 1, 0); PG8_STAGE(PG8_SA(0, 1), a2 + hstepA, voffA);
;             PG8_WAIT_V(8); PG8_WAIT_L(0); PG8_BAR; PG8_MMA(0, 0, At, B0); PG8_MMA(0, 1, At, B1); PG8_BAR; PG8_SCHED;
;             PG8_LDA(At, 1, 1); PG8_STAGE(PG8_SB(1, 0), b3, voffB); PG8_STAGE(PG8_SB(1, 1), b3 + hstepB, voffB); PG8_STAGE(PG8_SA(1, 0), a3, voffA);
;             PG8_WAIT_V(8); PG8_WAIT_L(0); PG8_BAR; PG8_MMA(1, 0, At, B0); PG8_MMA(1, 1, At, B1); PG8_BAR; PG8_SCHED;
;         }
	s_mov_b64 s[100:101], s[14:15]
	s_add_u32 s14, s14, 0x80000
	s_addc_u32 s15, s15, 0
	ds_read_b128 v[134:137], v185 offset:32768
	ds_read_b128 v[138:141], v185 offset:33792
	ds_read_b128 v[142:145], v185 offset:34816
	ds_read_b128 v[146:149], v185 offset:35840
	ds_read_b128 v[162:165], v185 offset:49152
	ds_read_b128 v[166:169], v185 offset:50176
	ds_read_b128 v[170:173], v185 offset:51200
	ds_read_b128 v[174:177], v185 offset:52224
	ds_read_b128 v[178:181], v186 offset:32768
	ds_read_b128 v[188:191], v186 offset:33792
	ds_read_b128 v[192:195], v186 offset:34816
	ds_read_b128 v[206:209], v186 offset:35840
	s_mov_b32 m0, s50
	ds_read_b128 v[224:227], v186 offset:36864
	global_load_lds_dwordx4 v150, s[100:101]
	s_mov_b32 m0, s51
	ds_read_b128 v[228:231], v186 offset:37888
	global_load_lds_dwordx4 v154, s[100:101]
	s_mov_b32 m0, s36
	ds_read_b128 v[232:235], v186 offset:38912
	global_load_lds_dwordx4 v150, s[14:15]
	s_mov_b32 m0, s37
	ds_read_b128 v[236:239], v186 offset:39936
	global_load_lds_dwordx4 v154, s[14:15]
	s_waitcnt vmcnt(8) lgkmcnt(0)
	s_barrier
	s_setprio 1
	v_mfma_f32_16x16x32_bf16 v[130:133], v[134:137], v[178:181], v[130:133]
	v_mfma_f32_16x16x32_bf16 v[126:129], v[142:145], v[178:181], v[126:129]
	v_mfma_f32_16x16x32_bf16 v[122:125], v[134:137], v[192:195], v[122:125]
	v_mfma_f32_16x16x32_bf16 v[118:121], v[142:145], v[192:195], v[118:121]
	v_mfma_f32_16x16x32_bf16 v[114:117], v[134:137], v[224:227], v[114:117]
	v_mfma_f32_16x16x32_bf16 v[110:113], v[142:145], v[224:227], v[110:113]
	v_mfma_f32_16x16x32_bf16 v[106:109], v[134:137], v[232:235], v[106:109]
	v_mfma_f32_16x16x32_bf16 v[102:105], v[142:145], v[232:235], v[102:105]
	v_mfma_f32_16x16x32_bf16 v[130:133], v[138:141], v[188:191], v[130:133]
	v_mfma_f32_16x16x32_bf16 v[126:129], v[146:149], v[188:191], v[126:129]
	v_mfma_f32_16x16x32_bf16 v[122:125], v[138:141], v[206:209], v[122:125]
	v_mfma_f32_16x16x32_bf16 v[118:121], v[146:149], v[206:209], v[118:121]
	v_mfma_f32_16x16x32_bf16 v[114:117], v[138:141], v[228:231], v[114:117]
	v_mfma_f32_16x16x32_bf16 v[110:113], v[146:149], v[228:231], v[110:113]
	v_mfma_f32_16x16x32_bf16 v[106:109], v[138:141], v[236:239], v[106:109]
	v_mfma_f32_16x16x32_bf16 v[102:105], v[146:149], v[236:239], v[102:105]
	s_setprio 0
	s_setprio 1
	v_mfma_f32_16x16x32_bf16 v[98:101], v[162:165], v[178:181], v[98:101]
	v_mfma_f32_16x16x32_bf16 v[94:97], v[170:173], v[178:181], v[94:97]
	v_mfma_f32_16x16x32_bf16 v[90:93], v[162:165], v[192:195], v[90:93]
	v_mfma_f32_16x16x32_bf16 v[86:89], v[170:173], v[192:195], v[86:89]
	v_mfma_f32_16x16x32_bf16 v[82:85], v[162:165], v[224:227], v[82:85]
	v_mfma_f32_16x16x32_bf16 v[78:81], v[170:173], v[224:227], v[78:81]
	v_mfma_f32_16x16x32_bf16 v[74:77], v[162:165], v[232:235], v[74:77]
	v_mfma_f32_16x16x32_bf16 v[70:73], v[170:173], v[232:235], v[70:73]
	v_mfma_f32_16x16x32_bf16 v[98:101], v[166:169], v[188:191], v[98:101]
	v_mfma_f32_16x16x32_bf16 v[94:97], v[174:177], v[188:191], v[94:97]
	v_mfma_f32_16x16x32_bf16 v[90:93], v[166:169], v[206:209], v[90:93]
	v_mfma_f32_16x16x32_bf16 v[86:89], v[174:177], v[206:209], v[86:89]
	v_mfma_f32_16x16x32_bf16 v[82:85], v[166:169], v[228:231], v[82:85]
	v_mfma_f32_16x16x32_bf16 v[78:81], v[174:177], v[228:231], v[78:81]
	v_mfma_f32_16x16x32_bf16 v[74:77], v[166:169], v[236:239], v[74:77]
	v_mfma_f32_16x16x32_bf16 v[70:73], v[174:177], v[236:239], v[70:73]
	s_setprio 0
	s_barrier
	ds_read_b128 v[178:181], v186 offset:49152
	ds_read_b128 v[188:191], v186 offset:50176
	ds_read_b128 v[192:195], v186 offset:51200
	ds_read_b128 v[206:209], v186 offset:52224
	s_add_i32 m0, s27, 0x17f80
	ds_read_b128 v[224:227], v186 offset:53248
	global_load_lds_dwordx4 v152, s[6:7] offset:128
	s_add_i32 m0, s27, 0x19f80
	ds_read_b128 v[228:231], v186 offset:54272
	global_load_lds_dwordx4 v156, s[6:7] offset:128
	s_add_i32 m0, s27, 0x1c000
	s_add_u32 s6, s6, 0x80080
	s_addc_u32 s7, s7, 0
	ds_read_b128 v[232:235], v186 offset:55296
	global_load_lds_dwordx4 v152, s[6:7]
	s_add_i32 m0, s27, 0x1e000
	ds_read_b128 v[236:239], v186 offset:56320
	global_load_lds_dwordx4 v156, s[6:7]
	s_cmp_ge_i32 s22, s46
	s_cbranch_scc0 .Lx4last_3
	s_add_i32 m0, s92, 0xffffff80
	s_nop 0
	global_load_lds_dwordx4 v150, s[100:101] offset:128
	s_add_i32 m0, s93, 0xffffff80
	s_nop 0
	global_load_lds_dwordx4 v154, s[100:101] offset:128
.Lx4last_3:
	s_waitcnt vmcnt(6) lgkmcnt(0)
	s_barrier
	s_setprio 1
	v_mfma_f32_16x16x32_bf16 v[66:69], v[134:137], v[178:181], v[66:69]
	v_mfma_f32_16x16x32_bf16 v[62:65], v[142:145], v[178:181], v[62:65]
	v_mfma_f32_16x16x32_bf16 v[58:61], v[134:137], v[192:195], v[58:61]
	v_mfma_f32_16x16x32_bf16 v[54:57], v[142:145], v[192:195], v[54:57]
	v_mfma_f32_16x16x32_bf16 v[50:53], v[134:137], v[224:227], v[50:53]
	v_mfma_f32_16x16x32_bf16 v[46:49], v[142:145], v[224:227], v[46:49]
	v_mfma_f32_16x16x32_bf16 v[42:45], v[134:137], v[232:235], v[42:45]
	v_mfma_f32_16x16x32_bf16 v[38:41], v[142:145], v[232:235], v[38:41]
	v_mfma_f32_16x16x32_bf16 v[66:69], v[138:141], v[188:191], v[66:69]
	v_mfma_f32_16x16x32_bf16 v[62:65], v[146:149], v[188:191], v[62:65]
	v_mfma_f32_16x16x32_bf16 v[58:61], v[138:141], v[206:209], v[58:61]
	v_mfma_f32_16x16x32_bf16 v[54:57], v[146:149], v[206:209], v[54:57]
	v_mfma_f32_16x16x32_bf16 v[50:53], v[138:141], v[228:231], v[50:53]
	v_mfma_f32_16x16x32_bf16 v[46:49], v[146:149], v[228:231], v[46:49]
	v_mfma_f32_16x16x32_bf16 v[42:45], v[138:141], v[236:239], v[42:45]
	v_mfma_f32_16x16x32_bf16 v[38:41], v[146:149], v[236:239], v[38:41]
	s_setprio 0
	s_setprio 1
	v_mfma_f32_16x16x32_bf16 v[34:37], v[162:165], v[178:181], v[34:37]
	v_mfma_f32_16x16x32_bf16 v[30:33], v[170:173], v[178:181], v[30:33]
	v_mfma_f32_16x16x32_bf16 v[26:29], v[162:165], v[192:195], v[26:29]
	v_mfma_f32_16x16x32_bf16 v[22:25], v[170:173], v[192:195], v[22:25]
	v_mfma_f32_16x16x32_bf16 v[18:21], v[162:165], v[224:227], v[18:21]
	v_mfma_f32_16x16x32_bf16 v[14:17], v[170:173], v[224:227], v[14:17]
	v_mfma_f32_16x16x32_bf16 v[8:11], v[162:165], v[232:235], v[10:13]
	v_mfma_f32_16x16x32_bf16 v[4:7], v[170:173], v[232:235], v[4:7]
	v_mfma_f32_16x16x32_bf16 v[34:37], v[166:169], v[188:191], v[34:37]
	v_mfma_f32_16x16x32_bf16 v[30:33], v[174:177], v[188:191], v[30:33]
	v_mfma_f32_16x16x32_bf16 v[26:29], v[166:169], v[206:209], v[26:29]
	v_mfma_f32_16x16x32_bf16 v[22:25], v[174:177], v[206:209], v[22:25]
	v_mfma_f32_16x16x32_bf16 v[18:21], v[166:169], v[228:231], v[18:21]
	v_mfma_f32_16x16x32_bf16 v[14:17], v[174:177], v[228:231], v[14:17]
	v_mfma_f32_16x16x32_bf16 v[10:13], v[166:169], v[236:239], v[8:11]
	v_mfma_f32_16x16x32_bf16 v[6:9], v[174:177], v[236:239], v[4:7]
	s_setprio 0
	s_barrier
	s_add_u32 s4, s4, 0x100
	s_addc_u32 s5, s5, 0
	s_add_u32 s20, s20, 0x100
	s_addc_u32 s21, s21, 0
	s_cmp_ge_i32 s22, s46
	s_mov_b32 s6, s22
	s_cbranch_scc0 .LBB0_500
	s_add_i32 s14, s27, 0x1c000
	s_mov_b32 s23, 0x18000
	s_mov_b32 s24, 0x1c000
	s_mov_b32 s52, 0x14000

; #define PG8_STAGE(bufoff, gbase, voff) do { _Pragma("unroll") for (int _i = 0; _i < 2; ++_i) \
;         __builtin_amdgcn_global_load_lds((const unsigned*)((const char*)(gbase) + (voff)[_i]), (LAS unsigned*)(lds + (bufoff) + ldsw + _i * 8192), 16, 0, 0); } while (0)
; #define PG8_LDA(dst, b, h) do { _Pragma("unroll") for (int m = 0; m < 4; ++m) _Pragma("unroll") for (int k = 0; k < 2; ++k) dst[m][k] = *(const LAS bf16x8*)(lds + PG8_SA(b, h) + aoff + m * 2048 + k * 1024); } while (0)
; #define PG8_LDB(dst, b, h) do { _Pragma("unroll") for (int n = 0; n < 2; ++n) _Pragma("unroll") for (int k = 0; k < 2; ++k) dst[n][k] = *(const LAS bf16x8*)(lds + PG8_SB(b, h) + boff + n * 2048 + k * 1024); } while (0)
; #define PG8_MMA(ai, bj, At, Bt) do { __builtin_amdgcn_s_setprio(1); _Pragma("unroll") for (int m = 0; m < 4; ++m) _Pragma("unroll") for (int n = 0; n < 2; ++n) _Pragma("unroll") for (int k = 0; k < 2; ++k) \
;         acc[ai][bj][m][n] = __builtin_amdgcn_mfma_f32_16x16x32_bf16(Bt[n][k], At[m][k], acc[ai][bj][m][n], 0, 0, 0); __builtin_amdgcn_s_setprio(0); } while (0)
; #define PG8_WAIT_V(n) asm volatile("s_waitcnt vmcnt(" #n ")" ::: "memory")
; #define PG8_WAIT_L(n) asm volatile("s_waitcnt lgkmcnt(" #n ")" ::: "memory")
; #define PG8_BAR __builtin_amdgcn_s_barrier()
; #define PG8_WAIT_RELAX(flag, n) asm volatile("s_cmp_eq_u32 %0, 0\n\ts_cbranch_scc1 .Lrw%=\n\ts_waitcnt vmcnt(8)\n.Lrw%=:\n\ts_waitcnt vmcnt(%1)" :: "s"(flag), "n"(n) : "scc", "memory")
; #define PG8_SCHED __builtin_amdgcn_sched_barrier(0)
; template <class Epi, bool ALIGN_EPI = true>
; __device__ __forceinline__ void gemm_phase(LAS unsigned char* lds, const Gemm g, const Sched& S, const Epi& E) {
;     ...
;             PG8_LDB(B0, 0, 0); PG8_LDB(B1, 0, 1); PG8_SCHED; PG8_LDA(At, 0, 0); PG8_STAGE(PG8_SA(1, 1), a1 + hstepA, voffA);
;             if constexpr (Epi::NSTORES > 0) PG8_WAIT_RELAX(rflag, 8 + Epi::NSTORES); else PG8_WAIT_V(8);
;             PG8_WAIT_L(0); PG8_BAR; PG8_MMA(0, 0, At, B0); PG8_MMA(0, 1, At, B1); PG8_BAR; PG8_SCHED;
;             PG8_LDA(At, 0, 1); PG8_STAGE(PG8_SB(0, 0), b2, voffB); PG8_STAGE(PG8_SB(0, 1), b2 + hstepB, voffB); PG8_STAGE(PG8_SA(0, 0), a2, voffA);
;             if constexpr (Epi::NSTORES > 0) PG8_WAIT_RELAX(rflag, 8 + Epi::NSTORES); else PG8_WAIT_V(8);
;             PG8_WAIT_L(0); PG8_BAR; PG8_MMA(1, 0, At, B0); PG8_MMA(1, 1, At, B1); PG8_BAR; PG8_SCHED;
.Lrw12:
	s_waitcnt vmcnt(24) lgkmcnt(0)
	s_barrier
	s_setprio 1
	v_mfma_f32_16x16x32_bf16 v[130:133], v[134:137], v[178:181], v[130:133]
	v_mfma_f32_16x16x32_bf16 v[126:129], v[142:145], v[178:181], v[126:129]
	v_mfma_f32_16x16x32_bf16 v[122:125], v[134:137], v[192:195], v[122:125]
	v_mfma_f32_16x16x32_bf16 v[118:121], v[142:145], v[192:195], v[118:121]
	v_mfma_f32_16x16x32_bf16 v[114:117], v[134:137], v[224:227], v[114:117]
	v_mfma_f32_16x16x32_bf16 v[110:113], v[142:145], v[224:227], v[110:113]
	v_mfma_f32_16x16x32_bf16 v[106:109], v[134:137], v[232:235], v[106:109]
	v_mfma_f32_16x16x32_bf16 v[102:105], v[142:145], v[232:235], v[102:105]
	v_mfma_f32_16x16x32_bf16 v[130:133], v[138:141], v[188:191], v[130:133]
	v_mfma_f32_16x16x32_bf16 v[126:129], v[146:149], v[188:191], v[126:129]
	v_mfma_f32_16x16x32_bf16 v[122:125], v[138:141], v[206:209], v[122:125]
	v_mfma_f32_16x16x32_bf16 v[118:121], v[146:149], v[206:209], v[118:121]
	v_mfma_f32_16x16x32_bf16 v[114:117], v[138:141], v[228:231], v[114:117]
	v_mfma_f32_16x16x32_bf16 v[110:113], v[146:149], v[228:231], v[110:113]
	v_mfma_f32_16x16x32_bf16 v[106:109], v[138:141], v[236:239], v[106:109]
	v_mfma_f32_16x16x32_bf16 v[102:105], v[146:149], v[236:239], v[102:105]
	s_setprio 0
	s_setprio 1
	v_mfma_f32_16x16x32_bf16 v[98:101], v[162:165], v[178:181], v[98:101]
	v_mfma_f32_16x16x32_bf16 v[94:97], v[170:173], v[178:181], v[94:97]
	v_mfma_f32_16x16x32_bf16 v[90:93], v[162:165], v[192:195], v[90:93]
	v_mfma_f32_16x16x32_bf16 v[86:89], v[170:173], v[192:195], v[86:89]
	v_mfma_f32_16x16x32_bf16 v[82:85], v[162:165], v[224:227], v[82:85]
	v_mfma_f32_16x16x32_bf16 v[78:81], v[170:173], v[224:227], v[78:81]
	v_mfma_f32_16x16x32_bf16 v[74:77], v[162:165], v[232:235], v[74:77]
	v_mfma_f32_16x16x32_bf16 v[70:73], v[170:173], v[232:235], v[70:73]
	v_mfma_f32_16x16x32_bf16 v[98:101], v[166:169], v[188:191], v[98:101]
	v_mfma_f32_16x16x32_bf16 v[94:97], v[174:177], v[188:191], v[94:97]
	v_mfma_f32_16x16x32_bf16 v[90:93], v[166:169], v[206:209], v[90:93]
	v_mfma_f32_16x16x32_bf16 v[86:89], v[174:177], v[206:209], v[86:89]
	v_mfma_f32_16x16x32_bf16 v[82:85], v[166:169], v[228:231], v[82:85]
	v_mfma_f32_16x16x32_bf16 v[78:81], v[174:177], v[228:231], v[78:81]
	v_mfma_f32_16x16x32_bf16 v[74:77], v[166:169], v[236:239], v[74:77]
	v_mfma_f32_16x16x32_bf16 v[70:73], v[174:177], v[236:239], v[70:73]
	s_setprio 0
	s_barrier
	s_add_u32 s24, s6, 0x80000
	s_addc_u32 s25, s7, 0
	ds_read_b128 v[178:181], v186 offset:16384
	ds_read_b128 v[188:191], v186 offset:17408
	ds_read_b128 v[192:195], v186 offset:18432
	ds_read_b128 v[206:209], v186 offset:19456
	s_add_i32 m0, s94, 0x10000
	ds_read_b128 v[224:227], v186 offset:20480
	global_load_lds_dwordx4 v152, s[6:7]
	s_add_i32 m0, s94, 0x12000
	ds_read_b128 v[228:231], v186 offset:21504
	global_load_lds_dwordx4 v156, s[6:7]
	s_add_i32 m0, s94, 0x14000
	ds_read_b128 v[232:235], v186 offset:22528
	global_load_lds_dwordx4 v152, s[24:25]
	s_add_i32 m0, s94, 0x16000
	ds_read_b128 v[236:239], v186 offset:23552
	global_load_lds_dwordx4 v156, s[24:25]
	s_cmp_eq_u32 s59, 0
	s_cbranch_scc1 .Lrw13
	s_waitcnt vmcnt(6)
.Lrw13:
	s_waitcnt vmcnt(24) lgkmcnt(0)
	s_barrier
	s_setprio 1
	v_mfma_f32_16x16x32_bf16 v[66:69], v[134:137], v[178:181], v[66:69]
	v_mfma_f32_16x16x32_bf16 v[62:65], v[142:145], v[178:181], v[62:65]
	v_mfma_f32_16x16x32_bf16 v[58:61], v[134:137], v[192:195], v[58:61]
	v_mfma_f32_16x16x32_bf16 v[54:57], v[142:145], v[192:195], v[54:57]
	v_mfma_f32_16x16x32_bf16 v[50:53], v[134:137], v[224:227], v[50:53]
	v_mfma_f32_16x16x32_bf16 v[46:49], v[142:145], v[224:227], v[46:49]
	v_mfma_f32_16x16x32_bf16 v[42:45], v[134:137], v[232:235], v[42:45]
	v_mfma_f32_16x16x32_bf16 v[38:41], v[142:145], v[232:235], v[38:41]
	v_mfma_f32_16x16x32_bf16 v[66:69], v[138:141], v[188:191], v[66:69]
	v_mfma_f32_16x16x32_bf16 v[62:65], v[146:149], v[188:191], v[62:65]
	v_mfma_f32_16x16x32_bf16 v[58:61], v[138:141], v[206:209], v[58:61]
	v_mfma_f32_16x16x32_bf16 v[54:57], v[146:149], v[206:209], v[54:57]
	v_mfma_f32_16x16x32_bf16 v[50:53], v[138:141], v[228:231], v[50:53]
	v_mfma_f32_16x16x32_bf16 v[46:49], v[146:149], v[228:231], v[46:49]
	v_mfma_f32_16x16x32_bf16 v[42:45], v[138:141], v[236:239], v[42:45]
	v_mfma_f32_16x16x32_bf16 v[38:41], v[146:149], v[236:239], v[38:41]
	s_setprio 0
	s_setprio 1
	v_mfma_f32_16x16x32_bf16 v[34:37], v[162:165], v[178:181], v[34:37]
	v_mfma_f32_16x16x32_bf16 v[30:33], v[170:173], v[178:181], v[30:33]
	v_mfma_f32_16x16x32_bf16 v[26:29], v[162:165], v[192:195], v[26:29]
	v_mfma_f32_16x16x32_bf16 v[22:25], v[170:173], v[192:195], v[22:25]
	v_mfma_f32_16x16x32_bf16 v[18:21], v[162:165], v[224:227], v[18:21]
	v_mfma_f32_16x16x32_bf16 v[14:17], v[170:173], v[224:227], v[14:17]
	v_mfma_f32_16x16x32_bf16 v[10:13], v[162:165], v[232:235], v[10:13]
	v_mfma_f32_16x16x32_bf16 v[4:7], v[170:173], v[232:235], v[6:9]
	v_mfma_f32_16x16x32_bf16 v[34:37], v[166:169], v[188:191], v[34:37]
	v_mfma_f32_16x16x32_bf16 v[30:33], v[174:177], v[188:191], v[30:33]
	v_mfma_f32_16x16x32_bf16 v[26:29], v[166:169], v[206:209], v[26:29]
	v_mfma_f32_16x16x32_bf16 v[22:25], v[174:177], v[206:209], v[22:25]
	v_mfma_f32_16x16x32_bf16 v[18:21], v[166:169], v[228:231], v[18:21]
	v_mfma_f32_16x16x32_bf16 v[14:17], v[174:177], v[228:231], v[14:17]
	v_mfma_f32_16x16x32_bf16 v[10:13], v[166:169], v[236:239], v[10:13]
	v_mfma_f32_16x16x32_bf16 v[4:7], v[174:177], v[236:239], v[4:7]
	s_setprio 0
	s_barrier
; #define PG8_STAGE(bufoff, gbase, voff) do { _Pragma("unroll") for (int _i = 0; _i < 2; ++_i) \
;         __builtin_amdgcn_global_load_lds((const unsigned*)((const char*)(gbase) + (voff)[_i]), (LAS unsigned*)(lds + (bufoff) + ldsw + _i * 8192), 16, 0, 0); } while (0)
; #define PG8_LDA(dst, b, h) do { _Pragma("unroll") for (int m = 0; m < 4; ++m) _Pragma("unroll") for (int k = 0; k < 2; ++k) dst[m][k] = *(const LAS bf16x8*)(lds + PG8_SA(b, h) + aoff + m * 2048 + k * 1024); } while (0)
; #define PG8_LDB(dst, b, h) do { _Pragma("unroll") for (int n = 0; n < 2; ++n) _Pragma("unroll") for (int k = 0; k < 2; ++k) dst[n][k] = *(const LAS bf16x8*)(lds + PG8_SB(b, h) + boff + n * 2048 + k * 1024); } while (0)
; #define PG8_MMA(ai, bj, At, Bt) do { __builtin_amdgcn_s_setprio(1); _Pragma("unroll") for (int m = 0; m < 4; ++m) _Pragma("unroll") for (int n = 0; n < 2; ++n) _Pragma("unroll") for (int k = 0; k < 2; ++k) \
;         acc[ai][bj][m][n] = __builtin_amdgcn_mfma_f32_16x16x32_bf16(Bt[n][k], At[m][k], acc[ai][bj][m][n], 0, 0, 0); __builtin_amdgcn_s_setprio(0); } while (0)
; #define PG8_WAIT_V(n) asm volatile("s_waitcnt vmcnt(" #n ")" ::: "memory")
; #define PG8_WAIT_L(n) asm volatile("s_waitcnt lgkmcnt(" #n ")" ::: "memory")
; #define PG8_BAR __builtin_amdgcn_s_barrier()
; #define PG8_SCHED __builtin_amdgcn_sched_barrier(0)
; template <class Epi, bool ALIGN_EPI = true>
; __device__ __forceinline__ void gemm_phase(LAS unsigned char* lds, const Gemm g, const Sched& S, const Epi& E) {
;     ...
;             PG8_LDB(B0, 1, 0); PG8_LDB(B1, 1, 1); PG8_SCHED; PG8_LDA(At, 1, 0); PG8_STAGE(PG8_SA(0, 1), a2 + hstepA, voffA);
;             PG8_WAIT_V(8); PG8_WAIT_L(0); PG8_BAR; PG8_MMA(0, 0, At, B0); PG8_MMA(0, 1, At, B1); PG8_BAR; PG8_SCHED;
;             PG8_LDA(At, 1, 1); PG8_STAGE(PG8_SB(1, 0), b3, voffB); PG8_STAGE(PG8_SB(1, 1), b3 + hstepB, voffB); PG8_STAGE(PG8_SA(1, 0), a3, voffA);
;             PG8_WAIT_V(8); PG8_WAIT_L(0); PG8_BAR; PG8_MMA(1, 0, At, B0); PG8_MMA(1, 1, At, B1); PG8_BAR; PG8_SCHED;
;         }
	s_mov_b64 s[100:101], s[14:15]
	s_add_u32 s14, s14, 0x80000
	s_addc_u32 s15, s15, 0
	ds_read_b128 v[134:137], v185 offset:32768
	ds_read_b128 v[138:141], v185 offset:33792
	ds_read_b128 v[142:145], v185 offset:34816
	ds_read_b128 v[146:149], v185 offset:35840
	ds_read_b128 v[162:165], v185 offset:49152
	ds_read_b128 v[166:169], v185 offset:50176
	ds_read_b128 v[170:173], v185 offset:51200
	ds_read_b128 v[174:177], v185 offset:52224
	ds_read_b128 v[178:181], v186 offset:32768
	ds_read_b128 v[188:191], v186 offset:33792
	ds_read_b128 v[192:195], v186 offset:34816
	ds_read_b128 v[206:209], v186 offset:35840
	s_mov_b32 m0, s48
	ds_read_b128 v[224:227], v186 offset:36864
	global_load_lds_dwordx4 v150, s[100:101]
	s_mov_b32 m0, s49
	ds_read_b128 v[228:231], v186 offset:37888
	global_load_lds_dwordx4 v154, s[100:101]
	s_mov_b32 m0, s46
	ds_read_b128 v[232:235], v186 offset:38912
	global_load_lds_dwordx4 v150, s[14:15]
	s_mov_b32 m0, s47
	ds_read_b128 v[236:239], v186 offset:39936
	global_load_lds_dwordx4 v154, s[14:15]
	s_waitcnt vmcnt(8) lgkmcnt(0)
	s_barrier
	s_setprio 1
	v_mfma_f32_16x16x32_bf16 v[130:133], v[134:137], v[178:181], v[130:133]
	v_mfma_f32_16x16x32_bf16 v[126:129], v[142:145], v[178:181], v[126:129]
	v_mfma_f32_16x16x32_bf16 v[122:125], v[134:137], v[192:195], v[122:125]
	v_mfma_f32_16x16x32_bf16 v[118:121], v[142:145], v[192:195], v[118:121]
	v_mfma_f32_16x16x32_bf16 v[114:117], v[134:137], v[224:227], v[114:117]
	v_mfma_f32_16x16x32_bf16 v[110:113], v[142:145], v[224:227], v[110:113]
	v_mfma_f32_16x16x32_bf16 v[106:109], v[134:137], v[232:235], v[106:109]
	v_mfma_f32_16x16x32_bf16 v[102:105], v[142:145], v[232:235], v[102:105]
	v_mfma_f32_16x16x32_bf16 v[130:133], v[138:141], v[188:191], v[130:133]
	v_mfma_f32_16x16x32_bf16 v[126:129], v[146:149], v[188:191], v[126:129]
	v_mfma_f32_16x16x32_bf16 v[122:125], v[138:141], v[206:209], v[122:125]
	v_mfma_f32_16x16x32_bf16 v[118:121], v[146:149], v[206:209], v[118:121]
	v_mfma_f32_16x16x32_bf16 v[114:117], v[138:141], v[228:231], v[114:117]
	v_mfma_f32_16x16x32_bf16 v[110:113], v[146:149], v[228:231], v[110:113]
	v_mfma_f32_16x16x32_bf16 v[106:109], v[138:141], v[236:239], v[106:109]
	v_mfma_f32_16x16x32_bf16 v[102:105], v[146:149], v[236:239], v[102:105]
	s_setprio 0
	s_setprio 1
	v_mfma_f32_16x16x32_bf16 v[98:101], v[162:165], v[178:181], v[98:101]
	v_mfma_f32_16x16x32_bf16 v[94:97], v[170:173], v[178:181], v[94:97]
	v_mfma_f32_16x16x32_bf16 v[90:93], v[162:165], v[192:195], v[90:93]
	v_mfma_f32_16x16x32_bf16 v[86:89], v[170:173], v[192:195], v[86:89]
	v_mfma_f32_16x16x32_bf16 v[82:85], v[162:165], v[224:227], v[82:85]
	v_mfma_f32_16x16x32_bf16 v[78:81], v[170:173], v[224:227], v[78:81]
	v_mfma_f32_16x16x32_bf16 v[74:77], v[162:165], v[232:235], v[74:77]
	v_mfma_f32_16x16x32_bf16 v[70:73], v[170:173], v[232:235], v[70:73]
	v_mfma_f32_16x16x32_bf16 v[98:101], v[166:169], v[188:191], v[98:101]
	v_mfma_f32_16x16x32_bf16 v[94:97], v[174:177], v[188:191], v[94:97]
	v_mfma_f32_16x16x32_bf16 v[90:93], v[166:169], v[206:209], v[90:93]
	v_mfma_f32_16x16x32_bf16 v[86:89], v[174:177], v[206:209], v[86:89]
	v_mfma_f32_16x16x32_bf16 v[82:85], v[166:169], v[228:231], v[82:85]
	v_mfma_f32_16x16x32_bf16 v[78:81], v[174:177], v[228:231], v[78:81]
	v_mfma_f32_16x16x32_bf16 v[74:77], v[166:169], v[236:239], v[74:77]
	v_mfma_f32_16x16x32_bf16 v[70:73], v[174:177], v[236:239], v[70:73]
	s_setprio 0
	s_barrier
	ds_read_b128 v[178:181], v186 offset:49152
	ds_read_b128 v[188:191], v186 offset:50176
	ds_read_b128 v[192:195], v186 offset:51200
	ds_read_b128 v[206:209], v186 offset:52224
	s_add_i32 m0, s94, 0x17f80
	ds_read_b128 v[224:227], v186 offset:53248
	global_load_lds_dwordx4 v152, s[6:7] offset:128
	s_add_i32 m0, s94, 0x19f80
	ds_read_b128 v[228:231], v186 offset:54272
	global_load_lds_dwordx4 v156, s[6:7] offset:128
	s_add_i32 m0, s94, 0x1c000
	s_add_u32 s6, s6, 0x80080
	s_addc_u32 s7, s7, 0
	ds_read_b128 v[232:235], v186 offset:55296
	global_load_lds_dwordx4 v152, s[6:7]
	s_add_i32 m0, s94, 0x1e000
	ds_read_b128 v[236:239], v186 offset:56320
	global_load_lds_dwordx4 v156, s[6:7]
	s_cmp_ge_i32 s22, s31
	s_cbranch_scc0 .Lx4last_6
	s_add_i32 m0, s30, 0xffffff80
	s_nop 0
	global_load_lds_dwordx4 v150, s[100:101] offset:128
	s_add_i32 m0, s33, 0xffffff80
	s_nop 0
	global_load_lds_dwordx4 v154, s[100:101] offset:128
.Lx4last_6:
	s_waitcnt vmcnt(6) lgkmcnt(0)
	s_barrier
	s_setprio 1
	v_mfma_f32_16x16x32_bf16 v[66:69], v[134:137], v[178:181], v[66:69]
	v_mfma_f32_16x16x32_bf16 v[62:65], v[142:145], v[178:181], v[62:65]
	v_mfma_f32_16x16x32_bf16 v[58:61], v[134:137], v[192:195], v[58:61]
	v_mfma_f32_16x16x32_bf16 v[54:57], v[142:145], v[192:195], v[54:57]
	v_mfma_f32_16x16x32_bf16 v[50:53], v[134:137], v[224:227], v[50:53]
	v_mfma_f32_16x16x32_bf16 v[46:49], v[142:145], v[224:227], v[46:49]
	v_mfma_f32_16x16x32_bf16 v[42:45], v[134:137], v[232:235], v[42:45]
	v_mfma_f32_16x16x32_bf16 v[38:41], v[142:145], v[232:235], v[38:41]
	v_mfma_f32_16x16x32_bf16 v[66:69], v[138:141], v[188:191], v[66:69]
	v_mfma_f32_16x16x32_bf16 v[62:65], v[146:149], v[188:191], v[62:65]
	v_mfma_f32_16x16x32_bf16 v[58:61], v[138:141], v[206:209], v[58:61]
	v_mfma_f32_16x16x32_bf16 v[54:57], v[146:149], v[206:209], v[54:57]
	v_mfma_f32_16x16x32_bf16 v[50:53], v[138:141], v[228:231], v[50:53]
	v_mfma_f32_16x16x32_bf16 v[46:49], v[146:149], v[228:231], v[46:49]
	v_mfma_f32_16x16x32_bf16 v[42:45], v[138:141], v[236:239], v[42:45]
	v_mfma_f32_16x16x32_bf16 v[38:41], v[146:149], v[236:239], v[38:41]
	s_setprio 0
	s_setprio 1
	v_mfma_f32_16x16x32_bf16 v[34:37], v[162:165], v[178:181], v[34:37]
	v_mfma_f32_16x16x32_bf16 v[30:33], v[170:173], v[178:181], v[30:33]
	v_mfma_f32_16x16x32_bf16 v[26:29], v[162:165], v[192:195], v[26:29]
	v_mfma_f32_16x16x32_bf16 v[22:25], v[170:173], v[192:195], v[22:25]
	v_mfma_f32_16x16x32_bf16 v[18:21], v[162:165], v[224:227], v[18:21]
	v_mfma_f32_16x16x32_bf16 v[14:17], v[170:173], v[224:227], v[14:17]
	v_mfma_f32_16x16x32_bf16 v[8:11], v[162:165], v[232:235], v[10:13]
	v_mfma_f32_16x16x32_bf16 v[4:7], v[170:173], v[232:235], v[4:7]
	v_mfma_f32_16x16x32_bf16 v[34:37], v[166:169], v[188:191], v[34:37]
	v_mfma_f32_16x16x32_bf16 v[30:33], v[174:177], v[188:191], v[30:33]
	v_mfma_f32_16x16x32_bf16 v[26:29], v[166:169], v[206:209], v[26:29]
	v_mfma_f32_16x16x32_bf16 v[22:25], v[174:177], v[206:209], v[22:25]
	v_mfma_f32_16x16x32_bf16 v[18:21], v[166:169], v[228:231], v[18:21]
	v_mfma_f32_16x16x32_bf16 v[14:17], v[174:177], v[228:231], v[14:17]
	v_mfma_f32_16x16x32_bf16 v[10:13], v[166:169], v[236:239], v[8:11]
	v_mfma_f32_16x16x32_bf16 v[6:9], v[174:177], v[236:239], v[4:7]
	s_setprio 0
	s_barrier
	s_add_u32 s4, s4, 0x100
	s_addc_u32 s5, s5, 0
	s_add_u32 s20, s20, 0x100
	s_addc_u32 s21, s21, 0
	s_cmp_ge_i32 s22, s31
	s_mov_b32 s6, s22
	s_cbranch_scc0 .LBB0_954
	s_add_i32 s14, s94, 0x1c000
	s_mov_b32 s23, 0x18000
	s_mov_b32 s24, 0x1c000
	s_mov_b32 s58, 0x14000

; #define PG8_STAGE(bufoff, gbase, voff) do { _Pragma("unroll") for (int _i = 0; _i < 2; ++_i) \
;         __builtin_amdgcn_global_load_lds((const unsigned*)((const char*)(gbase) + (voff)[_i]), (LAS unsigned*)(lds + (bufoff) + ldsw + _i * 8192), 16, 0, 0); } while (0)
; #define PG8_LDA(dst, b, h) do { _Pragma("unroll") for (int m = 0; m < 4; ++m) _Pragma("unroll") for (int k = 0; k < 2; ++k) dst[m][k] = *(const LAS bf16x8*)(lds + PG8_SA(b, h) + aoff + m * 2048 + k * 1024); } while (0)
; #define PG8_LDB(dst, b, h) do { _Pragma("unroll") for (int n = 0; n < 2; ++n) _Pragma("unroll") for (int k = 0; k < 2; ++k) dst[n][k] = *(const LAS bf16x8*)(lds + PG8_SB(b, h) + boff + n * 2048 + k * 1024); } while (0)
; #define PG8_MMA(ai, bj, At, Bt) do { __builtin_amdgcn_s_setprio(1); _Pragma("unroll") for (int m = 0; m < 4; ++m) _Pragma("unroll") for (int n = 0; n < 2; ++n) _Pragma("unroll") for (int k = 0; k < 2; ++k) \
;         acc[ai][bj][m][n] = __builtin_amdgcn_mfma_f32_16x16x32_bf16(Bt[n][k], At[m][k], acc[ai][bj][m][n], 0, 0, 0); __builtin_amdgcn_s_setprio(0); } while (0)
; #define PG8_WAIT_V(n) asm volatile("s_waitcnt vmcnt(" #n ")" ::: "memory")
; #define PG8_WAIT_L(n) asm volatile("s_waitcnt lgkmcnt(" #n ")" ::: "memory")
; #define PG8_BAR __builtin_amdgcn_s_barrier()
; #define PG8_WAIT_RELAX(flag, n) asm volatile("s_cmp_eq_u32 %0, 0\n\ts_cbranch_scc1 .Lrw%=\n\ts_waitcnt vmcnt(8)\n.Lrw%=:\n\ts_waitcnt vmcnt(%1)" :: "s"(flag), "n"(n) : "scc", "memory")
; #define PG8_SCHED __builtin_amdgcn_sched_barrier(0)
; template <class Epi, bool ALIGN_EPI = true>
; __device__ __forceinline__ void gemm_phase(LAS unsigned char* lds, const Gemm g, const Sched& S, const Epi& E) {
;     ...
;             PG8_LDB(B0, 0, 0); PG8_LDB(B1, 0, 1); PG8_SCHED; PG8_LDA(At, 0, 0); PG8_STAGE(PG8_SA(1, 1), a1 + hstepA, voffA);
;             if constexpr (Epi::NSTORES > 0) PG8_WAIT_RELAX(rflag, 8 + Epi::NSTORES); else PG8_WAIT_V(8);
;             PG8_WAIT_L(0); PG8_BAR; PG8_MMA(0, 0, At, B0); PG8_MMA(0, 1, At, B1); PG8_BAR; PG8_SCHED;
;             PG8_LDA(At, 0, 1); PG8_STAGE(PG8_SB(0, 0), b2, voffB); PG8_STAGE(PG8_SB(0, 1), b2 + hstepB, voffB); PG8_STAGE(PG8_SA(0, 0), a2, voffA);
;             if constexpr (Epi::NSTORES > 0) PG8_WAIT_RELAX(rflag, 8 + Epi::NSTORES); else PG8_WAIT_V(8);
;             PG8_WAIT_L(0); PG8_BAR; PG8_MMA(1, 0, At, B0); PG8_MMA(1, 1, At, B1); PG8_BAR; PG8_SCHED;
.Lrw18:
	s_waitcnt vmcnt(16) lgkmcnt(0)
	s_barrier
	s_setprio 1
	v_mfma_f32_16x16x32_bf16 v[130:133], v[146:149], v[182:185], v[130:133]
	v_mfma_f32_16x16x32_bf16 v[126:129], v[158:161], v[182:185], v[126:129]
	v_mfma_f32_16x16x32_bf16 v[122:125], v[146:149], v[190:193], v[122:125]
	v_mfma_f32_16x16x32_bf16 v[118:121], v[158:161], v[190:193], v[118:121]
	v_mfma_f32_16x16x32_bf16 v[114:117], v[146:149], v[206:209], v[114:117]
	v_mfma_f32_16x16x32_bf16 v[110:113], v[158:161], v[206:209], v[110:113]
	v_mfma_f32_16x16x32_bf16 v[106:109], v[146:149], v[228:231], v[106:109]
	v_mfma_f32_16x16x32_bf16 v[102:105], v[158:161], v[228:231], v[102:105]
	v_mfma_f32_16x16x32_bf16 v[130:133], v[154:157], v[186:189], v[130:133]
	v_mfma_f32_16x16x32_bf16 v[126:129], v[162:165], v[186:189], v[126:129]
	v_mfma_f32_16x16x32_bf16 v[122:125], v[154:157], v[194:197], v[122:125]
	v_mfma_f32_16x16x32_bf16 v[118:121], v[162:165], v[194:197], v[118:121]
	v_mfma_f32_16x16x32_bf16 v[114:117], v[154:157], v[224:227], v[114:117]
	v_mfma_f32_16x16x32_bf16 v[110:113], v[162:165], v[224:227], v[110:113]
	v_mfma_f32_16x16x32_bf16 v[106:109], v[154:157], v[232:235], v[106:109]
	v_mfma_f32_16x16x32_bf16 v[102:105], v[162:165], v[232:235], v[102:105]
	s_setprio 0
	s_setprio 1
	v_mfma_f32_16x16x32_bf16 v[98:101], v[166:169], v[182:185], v[98:101]
	v_mfma_f32_16x16x32_bf16 v[94:97], v[174:177], v[182:185], v[94:97]
	v_mfma_f32_16x16x32_bf16 v[90:93], v[166:169], v[190:193], v[90:93]
	v_mfma_f32_16x16x32_bf16 v[86:89], v[174:177], v[190:193], v[86:89]
	v_mfma_f32_16x16x32_bf16 v[82:85], v[166:169], v[206:209], v[82:85]
	v_mfma_f32_16x16x32_bf16 v[78:81], v[174:177], v[206:209], v[78:81]
	v_mfma_f32_16x16x32_bf16 v[74:77], v[166:169], v[228:231], v[74:77]
	v_mfma_f32_16x16x32_bf16 v[70:73], v[174:177], v[228:231], v[70:73]
	v_mfma_f32_16x16x32_bf16 v[98:101], v[170:173], v[186:189], v[98:101]
	v_mfma_f32_16x16x32_bf16 v[94:97], v[178:181], v[186:189], v[94:97]
	v_mfma_f32_16x16x32_bf16 v[90:93], v[170:173], v[194:197], v[90:93]
	v_mfma_f32_16x16x32_bf16 v[86:89], v[178:181], v[194:197], v[86:89]
	v_mfma_f32_16x16x32_bf16 v[82:85], v[170:173], v[224:227], v[82:85]
	v_mfma_f32_16x16x32_bf16 v[78:81], v[178:181], v[224:227], v[78:81]
	v_mfma_f32_16x16x32_bf16 v[74:77], v[170:173], v[232:235], v[74:77]
	v_mfma_f32_16x16x32_bf16 v[70:73], v[178:181], v[232:235], v[70:73]
	s_setprio 0
	s_barrier
	s_add_u32 s70, s46, 0x80000
	s_addc_u32 s71, s47, 0
	ds_read_b128 v[182:185], v152 offset:16384
	ds_read_b128 v[186:189], v152 offset:17408
	ds_read_b128 v[190:193], v152 offset:18432
	ds_read_b128 v[194:197], v152 offset:19456
	s_add_i32 m0, s35, 0x10000
	ds_read_b128 v[206:209], v152 offset:20480
	global_load_lds_dwordx4 v136, s[46:47]
	s_add_i32 m0, s35, 0x12000
	ds_read_b128 v[224:227], v152 offset:21504
	global_load_lds_dwordx4 v140, s[46:47]
	s_add_i32 m0, s35, 0x14000
	ds_read_b128 v[228:231], v152 offset:22528
	global_load_lds_dwordx4 v136, s[70:71]
	s_add_i32 m0, s35, 0x16000
	ds_read_b128 v[232:235], v152 offset:23552
	global_load_lds_dwordx4 v140, s[70:71]
	s_cmp_eq_u32 s73, 0
	s_cbranch_scc1 .Lrw19
	s_waitcnt vmcnt(6)
.Lrw19:
	s_waitcnt vmcnt(16) lgkmcnt(0)
	s_barrier
	s_setprio 1
	v_mfma_f32_16x16x32_bf16 v[66:69], v[146:149], v[182:185], v[66:69]
	v_mfma_f32_16x16x32_bf16 v[62:65], v[158:161], v[182:185], v[62:65]
	v_mfma_f32_16x16x32_bf16 v[58:61], v[146:149], v[190:193], v[58:61]
	v_mfma_f32_16x16x32_bf16 v[54:57], v[158:161], v[190:193], v[54:57]
	v_mfma_f32_16x16x32_bf16 v[50:53], v[146:149], v[206:209], v[50:53]
	v_mfma_f32_16x16x32_bf16 v[46:49], v[158:161], v[206:209], v[46:49]
	v_mfma_f32_16x16x32_bf16 v[42:45], v[146:149], v[228:231], v[42:45]
	v_mfma_f32_16x16x32_bf16 v[38:41], v[158:161], v[228:231], v[38:41]
	v_mfma_f32_16x16x32_bf16 v[66:69], v[154:157], v[186:189], v[66:69]
	v_mfma_f32_16x16x32_bf16 v[62:65], v[162:165], v[186:189], v[62:65]
	v_mfma_f32_16x16x32_bf16 v[58:61], v[154:157], v[194:197], v[58:61]
	v_mfma_f32_16x16x32_bf16 v[54:57], v[162:165], v[194:197], v[54:57]
	v_mfma_f32_16x16x32_bf16 v[50:53], v[154:157], v[224:227], v[50:53]
	v_mfma_f32_16x16x32_bf16 v[46:49], v[162:165], v[224:227], v[46:49]
	v_mfma_f32_16x16x32_bf16 v[42:45], v[154:157], v[232:235], v[42:45]
	v_mfma_f32_16x16x32_bf16 v[38:41], v[162:165], v[232:235], v[38:41]
	s_setprio 0
	s_setprio 1
	v_mfma_f32_16x16x32_bf16 v[34:37], v[166:169], v[182:185], v[34:37]
	v_mfma_f32_16x16x32_bf16 v[30:33], v[174:177], v[182:185], v[30:33]
	v_mfma_f32_16x16x32_bf16 v[26:29], v[166:169], v[190:193], v[26:29]
	v_mfma_f32_16x16x32_bf16 v[22:25], v[174:177], v[190:193], v[22:25]
	v_mfma_f32_16x16x32_bf16 v[18:21], v[166:169], v[206:209], v[18:21]
	v_mfma_f32_16x16x32_bf16 v[14:17], v[174:177], v[206:209], v[14:17]
	v_mfma_f32_16x16x32_bf16 v[10:13], v[166:169], v[228:231], v[10:13]
	v_mfma_f32_16x16x32_bf16 v[4:7], v[174:177], v[228:231], v[6:9]
	v_mfma_f32_16x16x32_bf16 v[34:37], v[170:173], v[186:189], v[34:37]
	v_mfma_f32_16x16x32_bf16 v[30:33], v[178:181], v[186:189], v[30:33]
	v_mfma_f32_16x16x32_bf16 v[26:29], v[170:173], v[194:197], v[26:29]
	v_mfma_f32_16x16x32_bf16 v[22:25], v[178:181], v[194:197], v[22:25]
	v_mfma_f32_16x16x32_bf16 v[18:21], v[170:173], v[224:227], v[18:21]
	v_mfma_f32_16x16x32_bf16 v[14:17], v[178:181], v[224:227], v[14:17]
	v_mfma_f32_16x16x32_bf16 v[10:13], v[170:173], v[232:235], v[10:13]
	v_mfma_f32_16x16x32_bf16 v[4:7], v[178:181], v[232:235], v[4:7]
	s_setprio 0
	s_barrier
; #define PG8_STAGE(bufoff, gbase, voff) do { _Pragma("unroll") for (int _i = 0; _i < 2; ++_i) \
;         __builtin_amdgcn_global_load_lds((const unsigned*)((const char*)(gbase) + (voff)[_i]), (LAS unsigned*)(lds + (bufoff) + ldsw + _i * 8192), 16, 0, 0); } while (0)
; #define PG8_LDA(dst, b, h) do { _Pragma("unroll") for (int m = 0; m < 4; ++m) _Pragma("unroll") for (int k = 0; k < 2; ++k) dst[m][k] = *(const LAS bf16x8*)(lds + PG8_SA(b, h) + aoff + m * 2048 + k * 1024); } while (0)
; #define PG8_LDB(dst, b, h) do { _Pragma("unroll") for (int n = 0; n < 2; ++n) _Pragma("unroll") for (int k = 0; k < 2; ++k) dst[n][k] = *(const LAS bf16x8*)(lds + PG8_SB(b, h) + boff + n * 2048 + k * 1024); } while (0)
; #define PG8_MMA(ai, bj, At, Bt) do { __builtin_amdgcn_s_setprio(1); _Pragma("unroll") for (int m = 0; m < 4; ++m) _Pragma("unroll") for (int n = 0; n < 2; ++n) _Pragma("unroll") for (int k = 0; k < 2; ++k) \
;         acc[ai][bj][m][n] = __builtin_amdgcn_mfma_f32_16x16x32_bf16(Bt[n][k], At[m][k], acc[ai][bj][m][n], 0, 0, 0); __builtin_amdgcn_s_setprio(0); } while (0)
; #define PG8_WAIT_V(n) asm volatile("s_waitcnt vmcnt(" #n ")" ::: "memory")
; #define PG8_WAIT_L(n) asm volatile("s_waitcnt lgkmcnt(" #n ")" ::: "memory")
; #define PG8_BAR __builtin_amdgcn_s_barrier()
; #define PG8_SCHED __builtin_amdgcn_sched_barrier(0)
; template <class Epi, bool ALIGN_EPI = true>
; __device__ __forceinline__ void gemm_phase(LAS unsigned char* lds, const Gemm g, const Sched& S, const Epi& E) {
;     ...
;             PG8_LDB(B0, 1, 0); PG8_LDB(B1, 1, 1); PG8_SCHED; PG8_LDA(At, 1, 0); PG8_STAGE(PG8_SA(0, 1), a2 + hstepA, voffA);
;             PG8_WAIT_V(8); PG8_WAIT_L(0); PG8_BAR; PG8_MMA(0, 0, At, B0); PG8_MMA(0, 1, At, B1); PG8_BAR; PG8_SCHED;
;             PG8_LDA(At, 1, 1); PG8_STAGE(PG8_SB(1, 0), b3, voffB); PG8_STAGE(PG8_SB(1, 1), b3 + hstepB, voffB); PG8_STAGE(PG8_SA(1, 0), a3, voffA);
;             PG8_WAIT_V(8); PG8_WAIT_L(0); PG8_BAR; PG8_MMA(1, 0, At, B0); PG8_MMA(1, 1, At, B1); PG8_BAR; PG8_SCHED;
;         }
	s_mov_b64 s[100:101], s[48:49]
	s_add_u32 s48, s48, 0x80000
	s_addc_u32 s49, s49, 0
	ds_read_b128 v[146:149], v151 offset:32768
	ds_read_b128 v[154:157], v151 offset:33792
	ds_read_b128 v[158:161], v151 offset:34816
	ds_read_b128 v[162:165], v151 offset:35840
	ds_read_b128 v[166:169], v151 offset:49152
	ds_read_b128 v[170:173], v151 offset:50176
	ds_read_b128 v[174:177], v151 offset:51200
	ds_read_b128 v[178:181], v151 offset:52224
	ds_read_b128 v[182:185], v152 offset:32768
	ds_read_b128 v[186:189], v152 offset:33792
	ds_read_b128 v[190:193], v152 offset:34816
	ds_read_b128 v[194:197], v152 offset:35840
	s_mov_b32 m0, s36
	ds_read_b128 v[206:209], v152 offset:36864
	global_load_lds_dwordx4 v134, s[100:101]
	s_mov_b32 m0, s37
	ds_read_b128 v[224:227], v152 offset:37888
	global_load_lds_dwordx4 v138, s[100:101]
	s_mov_b32 m0, s50
	ds_read_b128 v[228:231], v152 offset:38912
	global_load_lds_dwordx4 v134, s[48:49]
	s_mov_b32 m0, s51
	ds_read_b128 v[232:235], v152 offset:39936
	global_load_lds_dwordx4 v138, s[48:49]
	s_waitcnt vmcnt(8) lgkmcnt(0)
	s_barrier
	s_setprio 1
	v_mfma_f32_16x16x32_bf16 v[130:133], v[146:149], v[182:185], v[130:133]
	v_mfma_f32_16x16x32_bf16 v[126:129], v[158:161], v[182:185], v[126:129]
	v_mfma_f32_16x16x32_bf16 v[122:125], v[146:149], v[190:193], v[122:125]
	v_mfma_f32_16x16x32_bf16 v[118:121], v[158:161], v[190:193], v[118:121]
	v_mfma_f32_16x16x32_bf16 v[114:117], v[146:149], v[206:209], v[114:117]
	v_mfma_f32_16x16x32_bf16 v[110:113], v[158:161], v[206:209], v[110:113]
	v_mfma_f32_16x16x32_bf16 v[106:109], v[146:149], v[228:231], v[106:109]
	v_mfma_f32_16x16x32_bf16 v[102:105], v[158:161], v[228:231], v[102:105]
	v_mfma_f32_16x16x32_bf16 v[130:133], v[154:157], v[186:189], v[130:133]
	v_mfma_f32_16x16x32_bf16 v[126:129], v[162:165], v[186:189], v[126:129]
	v_mfma_f32_16x16x32_bf16 v[122:125], v[154:157], v[194:197], v[122:125]
	v_mfma_f32_16x16x32_bf16 v[118:121], v[162:165], v[194:197], v[118:121]
	v_mfma_f32_16x16x32_bf16 v[114:117], v[154:157], v[224:227], v[114:117]
	v_mfma_f32_16x16x32_bf16 v[110:113], v[162:165], v[224:227], v[110:113]
	v_mfma_f32_16x16x32_bf16 v[106:109], v[154:157], v[232:235], v[106:109]
	v_mfma_f32_16x16x32_bf16 v[102:105], v[162:165], v[232:235], v[102:105]
	s_setprio 0
	s_setprio 1
	v_mfma_f32_16x16x32_bf16 v[98:101], v[166:169], v[182:185], v[98:101]
	v_mfma_f32_16x16x32_bf16 v[94:97], v[174:177], v[182:185], v[94:97]
	v_mfma_f32_16x16x32_bf16 v[90:93], v[166:169], v[190:193], v[90:93]
	v_mfma_f32_16x16x32_bf16 v[86:89], v[174:177], v[190:193], v[86:89]
	v_mfma_f32_16x16x32_bf16 v[82:85], v[166:169], v[206:209], v[82:85]
	v_mfma_f32_16x16x32_bf16 v[78:81], v[174:177], v[206:209], v[78:81]
	v_mfma_f32_16x16x32_bf16 v[74:77], v[166:169], v[228:231], v[74:77]
	v_mfma_f32_16x16x32_bf16 v[70:73], v[174:177], v[228:231], v[70:73]
	v_mfma_f32_16x16x32_bf16 v[98:101], v[170:173], v[186:189], v[98:101]
	v_mfma_f32_16x16x32_bf16 v[94:97], v[178:181], v[186:189], v[94:97]
	v_mfma_f32_16x16x32_bf16 v[90:93], v[170:173], v[194:197], v[90:93]
	v_mfma_f32_16x16x32_bf16 v[86:89], v[178:181], v[194:197], v[86:89]
	v_mfma_f32_16x16x32_bf16 v[82:85], v[170:173], v[224:227], v[82:85]
	v_mfma_f32_16x16x32_bf16 v[78:81], v[178:181], v[224:227], v[78:81]
	v_mfma_f32_16x16x32_bf16 v[74:77], v[170:173], v[232:235], v[74:77]
	v_mfma_f32_16x16x32_bf16 v[70:73], v[178:181], v[232:235], v[70:73]
	s_setprio 0
	s_barrier
	ds_read_b128 v[182:185], v152 offset:49152
	ds_read_b128 v[186:189], v152 offset:50176
	ds_read_b128 v[190:193], v152 offset:51200
	ds_read_b128 v[194:197], v152 offset:52224
	s_add_i32 m0, s35, 0x17f80
	ds_read_b128 v[206:209], v152 offset:53248
	global_load_lds_dwordx4 v136, s[46:47] offset:128
	s_add_i32 m0, s35, 0x19f80
	ds_read_b128 v[224:227], v152 offset:54272
	global_load_lds_dwordx4 v140, s[46:47] offset:128
	s_add_i32 m0, s35, 0x1c000
	s_add_u32 s46, s46, 0x80080
	s_addc_u32 s47, s47, 0
	ds_read_b128 v[228:231], v152 offset:55296
	global_load_lds_dwordx4 v136, s[46:47]
	s_add_i32 m0, s35, 0x1e000
	ds_read_b128 v[232:235], v152 offset:56320
	global_load_lds_dwordx4 v140, s[46:47]
	s_cmp_ge_i32 s69, s54
	s_cbranch_scc0 .Lx4last_13
	s_add_i32 m0, s56, 0xffffff80
	s_nop 0
	global_load_lds_dwordx4 v134, s[100:101] offset:128
	s_add_i32 m0, s57, 0xffffff80
	s_nop 0
	global_load_lds_dwordx4 v138, s[100:101] offset:128
.Lx4last_13:
	s_waitcnt vmcnt(6) lgkmcnt(0)
	s_barrier
	s_setprio 1
	v_mfma_f32_16x16x32_bf16 v[66:69], v[146:149], v[182:185], v[66:69]
	v_mfma_f32_16x16x32_bf16 v[62:65], v[158:161], v[182:185], v[62:65]
	v_mfma_f32_16x16x32_bf16 v[58:61], v[146:149], v[190:193], v[58:61]
	v_mfma_f32_16x16x32_bf16 v[54:57], v[158:161], v[190:193], v[54:57]
	v_mfma_f32_16x16x32_bf16 v[50:53], v[146:149], v[206:209], v[50:53]
	v_mfma_f32_16x16x32_bf16 v[46:49], v[158:161], v[206:209], v[46:49]
	v_mfma_f32_16x16x32_bf16 v[42:45], v[146:149], v[228:231], v[42:45]
	v_mfma_f32_16x16x32_bf16 v[38:41], v[158:161], v[228:231], v[38:41]
	v_mfma_f32_16x16x32_bf16 v[66:69], v[154:157], v[186:189], v[66:69]
	v_mfma_f32_16x16x32_bf16 v[62:65], v[162:165], v[186:189], v[62:65]
	v_mfma_f32_16x16x32_bf16 v[58:61], v[154:157], v[194:197], v[58:61]
	v_mfma_f32_16x16x32_bf16 v[54:57], v[162:165], v[194:197], v[54:57]
	v_mfma_f32_16x16x32_bf16 v[50:53], v[154:157], v[224:227], v[50:53]
	v_mfma_f32_16x16x32_bf16 v[46:49], v[162:165], v[224:227], v[46:49]
	v_mfma_f32_16x16x32_bf16 v[42:45], v[154:157], v[232:235], v[42:45]
	v_mfma_f32_16x16x32_bf16 v[38:41], v[162:165], v[232:235], v[38:41]
	s_setprio 0
	s_setprio 1
	v_mfma_f32_16x16x32_bf16 v[34:37], v[166:169], v[182:185], v[34:37]
	v_mfma_f32_16x16x32_bf16 v[30:33], v[174:177], v[182:185], v[30:33]
	v_mfma_f32_16x16x32_bf16 v[26:29], v[166:169], v[190:193], v[26:29]
	v_mfma_f32_16x16x32_bf16 v[22:25], v[174:177], v[190:193], v[22:25]
	v_mfma_f32_16x16x32_bf16 v[18:21], v[166:169], v[206:209], v[18:21]
	v_mfma_f32_16x16x32_bf16 v[14:17], v[174:177], v[206:209], v[14:17]
	v_mfma_f32_16x16x32_bf16 v[8:11], v[166:169], v[228:231], v[10:13]
	v_mfma_f32_16x16x32_bf16 v[4:7], v[174:177], v[228:231], v[4:7]
	v_mfma_f32_16x16x32_bf16 v[34:37], v[170:173], v[186:189], v[34:37]
	v_mfma_f32_16x16x32_bf16 v[30:33], v[178:181], v[186:189], v[30:33]
	v_mfma_f32_16x16x32_bf16 v[26:29], v[170:173], v[194:197], v[26:29]
	v_mfma_f32_16x16x32_bf16 v[22:25], v[178:181], v[194:197], v[22:25]
	v_mfma_f32_16x16x32_bf16 v[18:21], v[170:173], v[224:227], v[18:21]
	v_mfma_f32_16x16x32_bf16 v[14:17], v[178:181], v[224:227], v[14:17]
	v_mfma_f32_16x16x32_bf16 v[10:13], v[170:173], v[232:235], v[8:11]
	v_mfma_f32_16x16x32_bf16 v[6:9], v[178:181], v[232:235], v[4:7]
	s_setprio 0
	s_barrier
	s_add_u32 s26, s26, 0x100
	s_addc_u32 s27, s27, 0
	s_add_u32 s67, s67, 0x100
	s_addc_u32 s68, s68, 0
	s_cmp_ge_i32 s69, s54
	s_mov_b32 s46, s69
	s_cbranch_scc0 .LBB0_2023
	s_add_i32 s48, s35, 0x1c000
	s_mov_b32 s70, 0x18000
	s_mov_b32 s71, 0x1c000
	s_add_i32 s72, s35, 0x14000
	s_mov_b32 s72, 0x8000
